# FFN-up epilogue: single weight wait before first store group instead of vmcnt(0) per group (no store drain between groups)
# speedup vs baseline: 1.0203x; 1.0052x over previous
;     __device__ __forceinline__ void operator()(const f32x4 (&acc)[2][2][4][2], const Unit& u, int wr, int wc, int fr, int fq) const {
;     ...
;         for (int ai = 0; ai < 2; ++ai)
; #pragma unroll
;             for (int m = 0; m < 4; ++m) {
;                 bool valid; int grow; bool zp = false, zn = false;
;                 if (!fix) { valid = !((ai == 0 && m == 0 && fr == 0) || (ai == 1 && m == 3 && fr == 15)); grow = u.pm * BM + wr * HALF + ai * 64 + m * 16 + fr; }
;                 else { const int R = (u.pm - nmain) * BM + wr * HALF + ai * 64 + m * 16 + fr; const int grp = R >> 2, pos = R & 3;
;                     const bool ss = (grp < 256) ? ((grp & 15) == 0) : (grp == 256);
;                     valid = (pos == 1) || (pos == 2); grow = (pos == 1) ? ((grp * 128 - 1 + mrows) % mrows) : (grp * 128);
;                     zn = (pos == 1) && ss; zp = (pos == 2) && ss; }
;                 f32x4 res[2];
;                 const float fzp = zp ? 0.f : 1.f, fzn = zn ? 0.f : 1.f;
; #pragma unroll
;                 for (int n = 0; n < 2; ++n) {
;                     const f32x4 g = acc[ai][0][m][n], up = acc[ai][1][m][n];
;                     f32x4 tp = g, tn = g;
;                     if (!fix) { const f32x4 gm = (m > 0) ? acc[ai][0][m - 1][n] : acc[ai ^ 1][0][3][n], gx = (m < 3) ? acc[ai][0][m + 1][n] : acc[ai ^ 1][0][0][n];
;                         tp = (fr == 15) ? gm : g; tn = (fr == 0) ? gx : g; }
;                     f32x4 gp, gn;
; #pragma unroll
;                     for (int j = 0; j < 4; ++j) { gp[j] = dpp_ror1(tp[j]); gn[j] = dpp_ror15(tn[j]); }
;                     const f32x4 cv = (w0[n] * fzp) * gp + (w1[n] * g + ((w2[n] * fzn) * gn + bb[n]));
;                     const f32x4 inner = cv * (cv * cv * 0.044715f + 1.0f) * (-2.0f * 0.7978845608028654f * 1.4426950408889634f);
;                     f32x4 sg;
; #pragma unroll
;                     for (int j = 0; j < 4; ++j) sg[j] = __builtin_amdgcn_rcpf(1.0f + __builtin_amdgcn_exp2f(inner[j]));
;                     res[n] = cv * sg * up;
;                 }
;                 if (valid) { u32x4 w; w.x = cvt_pk_bf16(res[0][0], res[0][1]); w.y = cvt_pk_bf16(res[0][2], res[0][3]); w.z = cvt_pk_bf16(res[1][0], res[1][1]); w.w = cvt_pk_bf16(res[1][2], res[1][3]);
;                     __builtin_nontemporal_store(w, (u32x4*)(ACT + (size_t)grow * 4096 + ch0)); }
.LBB0_631:
	s_and_b64 s[16:17], s[0:1], s[18:19]
	s_and_b64 s[18:19], s[4:5], s[18:19]
	v_cndmask_b32_e64 v188, v36, v140, s[18:19]
	v_cndmask_b32_e64 v184, v36, v12, s[16:17]
	v_cndmask_b32_e64 v185, v39, v143, s[18:19]
	v_cndmask_b32_e64 v186, v38, v142, s[18:19]
	v_cndmask_b32_e64 v187, v37, v141, s[18:19]
	v_mov_b32_dpp v196, v188 row_ror:15 row_mask:0xf bank_mask:0xf
	v_cndmask_b32_e64 v189, v28, v136, s[18:19]
	v_cndmask_b32_e64 v179, v39, v15, s[16:17]
	v_cndmask_b32_e64 v181, v38, v14, s[16:17]
	v_cndmask_b32_e64 v183, v37, v13, s[16:17]
	v_mov_b32_dpp v192, v184 row_ror:1 row_mask:0xf bank_mask:0xf
	v_mov_b32_dpp v197, v187 row_ror:15 row_mask:0xf bank_mask:0xf
	v_mov_b32_dpp v198, v186 row_ror:15 row_mask:0xf bank_mask:0xf
	v_mov_b32_dpp v199, v185 row_ror:15 row_mask:0xf bank_mask:0xf
	v_cndmask_b32_e64 v185, v28, v8, s[16:17]
	v_cndmask_b32_e64 v187, v30, v138, s[18:19]
	v_cndmask_b32_e64 v186, v29, v137, s[18:19]
	v_mov_b32_dpp v188, v189 row_ror:15 row_mask:0xf bank_mask:0xf
	v_mov_b32_dpp v193, v183 row_ror:1 row_mask:0xf bank_mask:0xf
	v_mov_b32_dpp v194, v181 row_ror:1 row_mask:0xf bank_mask:0xf
	v_mov_b32_dpp v195, v179 row_ror:1 row_mask:0xf bank_mask:0xf
	v_cndmask_b32_e64 v179, v31, v11, s[16:17]
	v_cndmask_b32_e64 v181, v30, v10, s[16:17]
	v_cndmask_b32_e64 v183, v29, v9, s[16:17]
	v_cndmask_b32_e64 v212, v31, v139, s[18:19]
	v_mov_b32_dpp v184, v185 row_ror:1 row_mask:0xf bank_mask:0xf
	v_mov_b32_dpp v189, v186 row_ror:15 row_mask:0xf bank_mask:0xf
	v_mov_b32_dpp v190, v187 row_ror:15 row_mask:0xf bank_mask:0xf
	v_mov_b32_dpp v185, v183 row_ror:1 row_mask:0xf bank_mask:0xf
	v_mov_b32_dpp v186, v181 row_ror:1 row_mask:0xf bank_mask:0xf
	v_mov_b32_dpp v187, v179 row_ror:1 row_mask:0xf bank_mask:0xf
	v_mov_b32_dpp v191, v212 row_ror:15 row_mask:0xf bank_mask:0xf
	s_waitcnt vmcnt(0)
	s_and_saveexec_b64 s[20:21], s[82:83]
	s_cbranch_execz .LBB0_633
	v_pk_mul_f32 v[218:219], v[96:97], v[180:181] op_sel_hi:[1,0]
	v_pk_mul_f32 v[214:215], v[88:89], v[182:183] op_sel_hi:[1,0]
	v_pk_fma_f32 v[196:197], v[218:219], v[196:197], v[100:101]
	v_pk_mul_f32 v[216:217], v[98:99], v[180:181] op_sel_hi:[1,0]
	v_pk_fma_f32 v[196:197], v[36:37], v[92:93], v[196:197]
	v_pk_fma_f32 v[198:199], v[216:217], v[198:199], v[102:103]
	v_pk_fma_f32 v[192:193], v[214:215], v[192:193], v[196:197]
	v_pk_mul_f32 v[212:213], v[90:91], v[182:183] op_sel_hi:[1,0]
	v_pk_mul_f32 v[196:197], v[192:193], v[192:193]
	v_pk_fma_f32 v[198:199], v[38:39], v[94:95], v[198:199]
	v_fma_f32 v179, v196, s97, 1.0
	v_mul_f32_e32 v179, v192, v179
	v_mul_f32_e32 v179, 0xc0135761, v179
	v_exp_f32_e32 v179, v179
	v_pk_fma_f32 v[194:195], v[212:213], v[194:195], v[198:199]
	v_add_f32_e32 v179, 1.0, v179
	v_pk_mul_f32 v[198:199], v[194:195], v[194:195]
	v_rcp_f32_e32 v196, v179
	v_fma_f32 v181, v198, s97, 1.0
	v_mul_f32_e32 v181, v194, v181
	v_fma_f32 v183, v199, s97, 1.0
	v_mul_f32_e32 v181, 0xc0135761, v181
	v_mul_f32_e32 v183, v195, v183
	v_fma_f32 v179, v197, s97, 1.0
	v_exp_f32_e32 v181, v181
	v_mul_f32_e32 v183, 0xc0135761, v183
	v_mul_f32_e32 v179, v193, v179
	v_exp_f32_e32 v183, v183
	v_mul_f32_e32 v179, 0xc0135761, v179
	v_exp_f32_e32 v179, v179
	v_add_f32_e32 v181, 1.0, v181
	v_rcp_f32_e32 v198, v181
	v_add_f32_e32 v181, 1.0, v183
	v_rcp_f32_e32 v199, v181
	v_add_f32_e32 v179, 1.0, v179
	v_rcp_f32_e32 v197, v179
	v_pk_mul_f32 v[194:195], v[194:195], v[198:199]
	v_pk_mul_f32 v[198:199], v[82:83], v[180:181] op_sel_hi:[1,0]
	v_pk_mul_f32 v[180:181], v[80:81], v[180:181] op_sel_hi:[1,0]
	v_pk_mul_f32 v[192:193], v[192:193], v[196:197]
	v_pk_fma_f32 v[180:181], v[180:181], v[188:189], v[84:85]
	v_pk_mul_f32 v[196:197], v[74:75], v[182:183] op_sel_hi:[1,0]
	v_pk_mul_f32 v[182:183], v[72:73], v[182:183] op_sel_hi:[1,0]
	v_pk_fma_f32 v[180:181], v[28:29], v[76:77], v[180:181]
	v_pk_fma_f32 v[190:191], v[198:199], v[190:191], v[86:87]
	v_pk_fma_f32 v[180:181], v[182:183], v[184:185], v[180:181]
	v_pk_fma_f32 v[184:185], v[30:31], v[78:79], v[190:191]
	v_pk_mul_f32 v[182:183], v[180:181], v[180:181]
	v_pk_fma_f32 v[184:185], v[196:197], v[186:187], v[184:185]
	v_fma_f32 v179, v182, s97, 1.0
	v_mul_f32_e32 v179, v180, v179
	v_mul_f32_e32 v179, 0xc0135761, v179
	v_exp_f32_e32 v179, v179
	v_pk_mul_f32 v[186:187], v[184:185], v[184:185]
	v_pk_mul_f32 v[156:157], v[156:157], v[192:193]
	v_pk_mul_f32 v[158:159], v[158:159], v[194:195]
	v_add_f32_e32 v179, 1.0, v179
	v_rcp_f32_e32 v182, v179
	v_fma_f32 v179, v183, s97, 1.0
	v_fma_f32 v183, v186, s97, 1.0
	v_mul_f32_e32 v183, v184, v183
	v_fma_f32 v186, v187, s97, 1.0
	v_mul_f32_e32 v179, v181, v179
	v_mul_f32_e32 v183, 0xc0135761, v183
	v_mul_f32_e32 v186, v185, v186
	v_mul_f32_e32 v179, 0xc0135761, v179
	v_exp_f32_e32 v183, v183
	v_mul_f32_e32 v186, 0xc0135761, v186
	v_exp_f32_e32 v179, v179
	v_exp_f32_e32 v187, v186
	v_add_f32_e32 v183, 1.0, v183
	v_rcp_f32_e32 v186, v183
	v_add_f32_e32 v179, 1.0, v179
	v_add_f32_e32 v183, 1.0, v187
	v_rcp_f32_e32 v187, v183
	v_rcp_f32_e32 v183, v179
	v_ashrrev_i32_e32 v179, 31, v178
	v_pk_mul_f32 v[184:185], v[184:185], v[186:187]
	v_pk_mul_f32 v[180:181], v[180:181], v[182:183]
	v_pk_mul_f32 v[182:183], v[154:155], v[184:185]
	v_pk_mul_f32 v[154:155], v[152:153], v[180:181]
	v_cvt_pk_bf16_f32 v152, v156, v157
	v_lshlrev_b64 v[156:157], 13, v[178:179]
	v_lshl_add_u64 v[156:157], s[44:45], 0, v[156:157]
	v_lshl_add_u64 v[156:157], v[176:177], 1, v[156:157]
	v_cvt_pk_bf16_f32 v153, v158, v159
	v_cvt_pk_bf16_f32 v154, v154, v155
	v_cvt_pk_bf16_f32 v155, v182, v183
	global_store_dwordx4 v[156:157], v[152:155], off nt

;     __device__ __forceinline__ void operator()(const f32x4 (&acc)[2][2][4][2], const Unit& u, int wr, int wc, int fr, int fq) const {
;     ...
;         for (int ai = 0; ai < 2; ++ai)
; #pragma unroll
;             for (int m = 0; m < 4; ++m) {
;                 bool valid; int grow; bool zp = false, zn = false;
;                 if (!fix) { valid = !((ai == 0 && m == 0 && fr == 0) || (ai == 1 && m == 3 && fr == 15)); grow = u.pm * BM + wr * HALF + ai * 64 + m * 16 + fr; }
;                 else { const int R = (u.pm - nmain) * BM + wr * HALF + ai * 64 + m * 16 + fr; const int grp = R >> 2, pos = R & 3;
;                     const bool ss = (grp < 256) ? ((grp & 15) == 0) : (grp == 256);
;                     valid = (pos == 1) || (pos == 2); grow = (pos == 1) ? ((grp * 128 - 1 + mrows) % mrows) : (grp * 128);
;                     zn = (pos == 1) && ss; zp = (pos == 2) && ss; }
;                 f32x4 res[2];
;                 const float fzp = zp ? 0.f : 1.f, fzn = zn ? 0.f : 1.f;
; #pragma unroll
;                 for (int n = 0; n < 2; ++n) {
;                     const f32x4 g = acc[ai][0][m][n], up = acc[ai][1][m][n];
;                     f32x4 tp = g, tn = g;
;                     if (!fix) { const f32x4 gm = (m > 0) ? acc[ai][0][m - 1][n] : acc[ai ^ 1][0][3][n], gx = (m < 3) ? acc[ai][0][m + 1][n] : acc[ai ^ 1][0][0][n];
;                         tp = (fr == 15) ? gm : g; tn = (fr == 0) ? gx : g; }
;                     f32x4 gp, gn;
; #pragma unroll
;                     for (int j = 0; j < 4; ++j) { gp[j] = dpp_ror1(tp[j]); gn[j] = dpp_ror15(tn[j]); }
;                     const f32x4 cv = (w0[n] * fzp) * gp + (w1[n] * g + ((w2[n] * fzn) * gn + bb[n]));
;                     const f32x4 inner = cv * (cv * cv * 0.044715f + 1.0f) * (-2.0f * 0.7978845608028654f * 1.4426950408889634f);
;                     f32x4 sg;
; #pragma unroll
;                     for (int j = 0; j < 4; ++j) sg[j] = __builtin_amdgcn_rcpf(1.0f + __builtin_amdgcn_exp2f(inner[j]));
;                     res[n] = cv * sg * up;
;                 }
;                 if (valid) { u32x4 w; w.x = cvt_pk_bf16(res[0][0], res[0][1]); w.y = cvt_pk_bf16(res[0][2], res[0][3]); w.z = cvt_pk_bf16(res[1][0], res[1][1]); w.w = cvt_pk_bf16(res[1][2], res[1][3]);
;                     __builtin_nontemporal_store(w, (u32x4*)(ACT + (size_t)grow * 4096 + ch0)); }
.LBB0_639:
	v_cndmask_b32_e64 v154, v142, v38, s[16:17]
	v_cndmask_b32_e64 v155, v141, v37, s[16:17]
	v_cndmask_b32_e64 v158, v142, v126, s[18:19]
	v_cndmask_b32_e64 v159, v141, v125, s[18:19]
	v_cndmask_b32_e64 v156, v140, v36, s[16:17]
	v_cndmask_b32_e64 v178, v140, v124, s[18:19]
	v_mov_b32_dpp v181, v155 row_ror:1 row_mask:0xf bank_mask:0xf
	v_mov_b32_dpp v185, v159 row_ror:15 row_mask:0xf bank_mask:0xf
	v_mov_b32_dpp v182, v154 row_ror:1 row_mask:0xf bank_mask:0xf
	v_mov_b32_dpp v186, v158 row_ror:15 row_mask:0xf bank_mask:0xf
	v_cndmask_b32_e64 v155, v136, v28, s[16:17]
	v_cndmask_b32_e64 v159, v136, v120, s[18:19]
	v_cndmask_b32_e64 v157, v143, v127, s[18:19]
	v_mov_b32_dpp v180, v156 row_ror:1 row_mask:0xf bank_mask:0xf
	v_mov_b32_dpp v184, v178 row_ror:15 row_mask:0xf bank_mask:0xf
	v_cndmask_b32_e64 v156, v137, v29, s[16:17]
	v_cndmask_b32_e64 v178, v137, v121, s[18:19]
	v_mov_b32_dpp v154, v155 row_ror:1 row_mask:0xf bank_mask:0xf
	v_mov_b32_dpp v158, v159 row_ror:15 row_mask:0xf bank_mask:0xf
	v_cndmask_b32_e64 v153, v143, v39, s[16:17]
	v_mov_b32_dpp v187, v157 row_ror:15 row_mask:0xf bank_mask:0xf
	v_cndmask_b32_e64 v157, v138, v30, s[16:17]
	v_cndmask_b32_e64 v179, v138, v122, s[18:19]
	v_mov_b32_dpp v155, v156 row_ror:1 row_mask:0xf bank_mask:0xf
	v_mov_b32_dpp v159, v178 row_ror:15 row_mask:0xf bank_mask:0xf
	v_mov_b32_dpp v183, v153 row_ror:1 row_mask:0xf bank_mask:0xf
	v_cndmask_b32_e64 v153, v139, v31, s[16:17]
	v_cndmask_b32_e64 v189, v139, v123, s[18:19]
	v_mov_b32_dpp v156, v157 row_ror:1 row_mask:0xf bank_mask:0xf
	v_mov_b32_dpp v178, v179 row_ror:15 row_mask:0xf bank_mask:0xf
	s_nop 0
	v_mov_b32_dpp v157, v153 row_ror:1 row_mask:0xf bank_mask:0xf
	v_mov_b32_dpp v179, v189 row_ror:15 row_mask:0xf bank_mask:0xf
	s_and_saveexec_b64 s[80:81], s[82:83]
	s_cbranch_execz .LBB0_641
	v_pk_fma_f32 v[184:185], v[96:97], v[184:185], v[100:101]
	v_pk_fma_f32 v[186:187], v[98:99], v[186:187], v[102:103]
	v_pk_fma_f32 v[184:185], v[140:141], v[92:93], v[184:185]
	v_pk_fma_f32 v[186:187], v[142:143], v[94:95], v[186:187]
	v_pk_fma_f32 v[180:181], v[88:89], v[180:181], v[184:185]
	v_pk_fma_f32 v[182:183], v[90:91], v[182:183], v[186:187]
	v_pk_mul_f32 v[184:185], v[180:181], v[180:181]
	v_pk_mul_f32 v[186:187], v[182:183], v[182:183]
	v_fma_f32 v153, v184, s97, 1.0
	v_mul_f32_e32 v153, v180, v153
	v_mul_f32_e32 v153, 0xc0135761, v153
	v_exp_f32_e32 v153, v153
	v_pk_fma_f32 v[158:159], v[80:81], v[158:159], v[84:85]
	v_pk_fma_f32 v[178:179], v[82:83], v[178:179], v[86:87]
	v_pk_fma_f32 v[158:159], v[136:137], v[76:77], v[158:159]
	v_add_f32_e32 v153, 1.0, v153
	v_rcp_f32_e32 v184, v153
	v_fma_f32 v153, v185, s97, 1.0
	v_fma_f32 v185, v186, s97, 1.0
	v_mul_f32_e32 v185, v182, v185
	v_fma_f32 v186, v187, s97, 1.0
	v_mul_f32_e32 v153, v181, v153
	v_mul_f32_e32 v185, 0xc0135761, v185
	v_mul_f32_e32 v186, v183, v186
	v_mul_f32_e32 v153, 0xc0135761, v153
	v_exp_f32_e32 v185, v185
	v_mul_f32_e32 v186, 0xc0135761, v186
	v_exp_f32_e32 v153, v153
	v_exp_f32_e32 v187, v186
	v_add_f32_e32 v185, 1.0, v185
	v_pk_fma_f32 v[154:155], v[72:73], v[154:155], v[158:159]
	v_add_f32_e32 v153, 1.0, v153
	v_rcp_f32_e32 v186, v185
	v_add_f32_e32 v185, 1.0, v187
	v_pk_mul_f32 v[158:159], v[154:155], v[154:155]
	v_rcp_f32_e32 v187, v185
	v_rcp_f32_e32 v185, v153
	v_fma_f32 v153, v158, s97, 1.0
	v_mul_f32_e32 v153, v154, v153
	v_mul_f32_e32 v153, 0xc0135761, v153
	v_exp_f32_e32 v153, v153
	v_pk_fma_f32 v[178:179], v[138:139], v[78:79], v[178:179]
	v_pk_mul_f32 v[180:181], v[180:181], v[184:185]
	v_pk_fma_f32 v[156:157], v[74:75], v[156:157], v[178:179]
	v_add_f32_e32 v153, 1.0, v153
	v_pk_mul_f32 v[178:179], v[156:157], v[156:157]
	v_rcp_f32_e32 v158, v153
	v_fma_f32 v153, v159, s97, 1.0
	v_fma_f32 v159, v178, s97, 1.0
	v_mul_f32_e32 v159, v156, v159
	v_fma_f32 v178, v179, s97, 1.0
	v_mul_f32_e32 v153, v155, v153
	v_mul_f32_e32 v159, 0xc0135761, v159
	v_mul_f32_e32 v178, v157, v178
	v_mul_f32_e32 v153, 0xc0135761, v153
	v_exp_f32_e32 v159, v159
	v_mul_f32_e32 v178, 0xc0135761, v178
	v_exp_f32_e32 v153, v153
	v_exp_f32_e32 v179, v178
	v_add_f32_e32 v159, 1.0, v159
	v_rcp_f32_e32 v178, v159
	v_add_f32_e32 v153, 1.0, v153
	v_add_f32_e32 v159, 1.0, v179
	v_rcp_f32_e32 v179, v159
	v_rcp_f32_e32 v159, v153
	v_pk_mul_f32 v[148:149], v[148:149], v[180:181]
	v_ashrrev_i32_e32 v153, 31, v152
	v_pk_mul_f32 v[156:157], v[156:157], v[178:179]
	v_pk_mul_f32 v[154:155], v[154:155], v[158:159]
	v_pk_mul_f32 v[156:157], v[146:147], v[156:157]
	v_pk_mul_f32 v[146:147], v[144:145], v[154:155]
	v_cvt_pk_bf16_f32 v144, v148, v149
	v_lshlrev_b64 v[148:149], 13, v[152:153]
	v_lshl_add_u64 v[148:149], s[44:45], 0, v[148:149]
	v_pk_mul_f32 v[182:183], v[182:183], v[186:187]
	v_lshl_add_u64 v[148:149], v[176:177], 1, v[148:149]
	v_pk_mul_f32 v[150:151], v[150:151], v[182:183]
	s_nop 0
	v_cvt_pk_bf16_f32 v145, v150, v151
	v_cvt_pk_bf16_f32 v146, v146, v147
	v_cvt_pk_bf16_f32 v147, v156, v157
	global_store_dwordx4 v[148:149], v[144:147], off nt

;     __device__ __forceinline__ void operator()(const f32x4 (&acc)[2][2][4][2], const Unit& u, int wr, int wc, int fr, int fq) const {
;     ...
;         for (int ai = 0; ai < 2; ++ai)
; #pragma unroll
;             for (int m = 0; m < 4; ++m) {
;                 bool valid; int grow; bool zp = false, zn = false;
;                 if (!fix) { valid = !((ai == 0 && m == 0 && fr == 0) || (ai == 1 && m == 3 && fr == 15)); grow = u.pm * BM + wr * HALF + ai * 64 + m * 16 + fr; }
;                 else { const int R = (u.pm - nmain) * BM + wr * HALF + ai * 64 + m * 16 + fr; const int grp = R >> 2, pos = R & 3;
;                     const bool ss = (grp < 256) ? ((grp & 15) == 0) : (grp == 256);
;                     valid = (pos == 1) || (pos == 2); grow = (pos == 1) ? ((grp * 128 - 1 + mrows) % mrows) : (grp * 128);
;                     zn = (pos == 1) && ss; zp = (pos == 2) && ss; }
;                 f32x4 res[2];
;                 const float fzp = zp ? 0.f : 1.f, fzn = zn ? 0.f : 1.f;
; #pragma unroll
;                 for (int n = 0; n < 2; ++n) {
;                     const f32x4 g = acc[ai][0][m][n], up = acc[ai][1][m][n];
;                     f32x4 tp = g, tn = g;
;                     if (!fix) { const f32x4 gm = (m > 0) ? acc[ai][0][m - 1][n] : acc[ai ^ 1][0][3][n], gx = (m < 3) ? acc[ai][0][m + 1][n] : acc[ai ^ 1][0][0][n];
;                         tp = (fr == 15) ? gm : g; tn = (fr == 0) ? gx : g; }
;                     f32x4 gp, gn;
; #pragma unroll
;                     for (int j = 0; j < 4; ++j) { gp[j] = dpp_ror1(tp[j]); gn[j] = dpp_ror15(tn[j]); }
;                     const f32x4 cv = (w0[n] * fzp) * gp + (w1[n] * g + ((w2[n] * fzn) * gn + bb[n]));
;                     const f32x4 inner = cv * (cv * cv * 0.044715f + 1.0f) * (-2.0f * 0.7978845608028654f * 1.4426950408889634f);
;                     f32x4 sg;
; #pragma unroll
;                     for (int j = 0; j < 4; ++j) sg[j] = __builtin_amdgcn_rcpf(1.0f + __builtin_amdgcn_exp2f(inner[j]));
;                     res[n] = cv * sg * up;
;                 }
;                 if (valid) { u32x4 w; w.x = cvt_pk_bf16(res[0][0], res[0][1]); w.y = cvt_pk_bf16(res[0][2], res[0][3]); w.z = cvt_pk_bf16(res[1][0], res[1][1]); w.w = cvt_pk_bf16(res[1][2], res[1][3]);
;                     __builtin_nontemporal_store(w, (u32x4*)(ACT + (size_t)grow * 4096 + ch0)); }
.LBB0_647:
	v_cndmask_b32_e64 v149, v126, v110, s[18:19]
	v_cndmask_b32_e64 v143, v127, v143, s[16:17]
	v_cndmask_b32_e64 v147, v124, v108, s[18:19]
	v_mov_b32_dpp v152, v149 row_ror:15 row_mask:0xf bank_mask:0xf
	v_cndmask_b32_e64 v141, v125, v141, s[16:17]
	v_mov_b32_dpp v149, v143 row_ror:1 row_mask:0xf bank_mask:0xf
	v_cndmask_b32_e64 v143, v123, v139, s[16:17]
	v_cndmask_b32_e64 v139, v122, v138, s[16:17]
	v_cndmask_b32_e64 v138, v121, v137, s[16:17]
	v_cndmask_b32_e64 v137, v120, v136, s[16:17]
	v_cndmask_b32_e64 v140, v124, v140, s[16:17]
	v_cndmask_b32_e64 v148, v125, v109, s[18:19]
	v_mov_b32_dpp v150, v147 row_ror:15 row_mask:0xf bank_mask:0xf
	v_mov_b32_dpp v136, v137 row_ror:1 row_mask:0xf bank_mask:0xf
	v_cndmask_b32_e64 v142, v126, v142, s[16:17]
	v_mov_b32_dpp v146, v140 row_ror:1 row_mask:0xf bank_mask:0xf
	v_mov_b32_dpp v147, v141 row_ror:1 row_mask:0xf bank_mask:0xf
	v_mov_b32_dpp v151, v148 row_ror:15 row_mask:0xf bank_mask:0xf
	v_cndmask_b32_e64 v141, v120, v104, s[18:19]
	v_mov_b32_dpp v137, v138 row_ror:1 row_mask:0xf bank_mask:0xf
	v_cndmask_b32_e64 v145, v127, v111, s[18:19]
	v_mov_b32_dpp v148, v142 row_ror:1 row_mask:0xf bank_mask:0xf
	v_cndmask_b32_e64 v142, v121, v105, s[18:19]
	v_mov_b32_dpp v140, v141 row_ror:15 row_mask:0xf bank_mask:0xf
	v_mov_b32_dpp v138, v139 row_ror:1 row_mask:0xf bank_mask:0xf
	v_mov_b32_dpp v153, v145 row_ror:15 row_mask:0xf bank_mask:0xf
	v_cndmask_b32_e64 v145, v123, v107, s[18:19]
	v_cndmask_b32_e64 v154, v122, v106, s[18:19]
	v_mov_b32_dpp v141, v142 row_ror:15 row_mask:0xf bank_mask:0xf
	v_mov_b32_dpp v139, v143 row_ror:1 row_mask:0xf bank_mask:0xf
	v_mov_b32_dpp v142, v154 row_ror:15 row_mask:0xf bank_mask:0xf
	s_nop 0
	v_mov_b32_dpp v143, v145 row_ror:15 row_mask:0xf bank_mask:0xf
	s_and_saveexec_b64 s[80:81], s[82:83]
	s_cbranch_execz .LBB0_649
	v_pk_fma_f32 v[150:151], v[96:97], v[150:151], v[100:101]
	v_pk_fma_f32 v[152:153], v[98:99], v[152:153], v[102:103]
	v_pk_fma_f32 v[150:151], v[124:125], v[92:93], v[150:151]
	v_pk_fma_f32 v[152:153], v[126:127], v[94:95], v[152:153]
	v_pk_fma_f32 v[146:147], v[88:89], v[146:147], v[150:151]
	v_pk_fma_f32 v[148:149], v[90:91], v[148:149], v[152:153]
	v_pk_mul_f32 v[150:151], v[146:147], v[146:147]
	v_pk_fma_f32 v[142:143], v[82:83], v[142:143], v[86:87]
	v_fma_f32 v145, v150, s97, 1.0
	v_mul_f32_e32 v145, v146, v145
	v_mul_f32_e32 v145, 0xc0135761, v145
	v_exp_f32_e32 v145, v145
	v_pk_fma_f32 v[140:141], v[80:81], v[140:141], v[84:85]
	v_pk_mul_f32 v[152:153], v[148:149], v[148:149]
	v_pk_fma_f32 v[140:141], v[120:121], v[76:77], v[140:141]
	v_add_f32_e32 v145, 1.0, v145
	v_pk_fma_f32 v[142:143], v[122:123], v[78:79], v[142:143]
	v_rcp_f32_e32 v150, v145
	v_fma_f32 v145, v151, s97, 1.0
	v_fma_f32 v151, v152, s97, 1.0
	v_pk_fma_f32 v[136:137], v[72:73], v[136:137], v[140:141]
	v_pk_fma_f32 v[138:139], v[74:75], v[138:139], v[142:143]
	v_mul_f32_e32 v151, v148, v151
	v_fma_f32 v152, v153, s97, 1.0
	v_pk_mul_f32 v[140:141], v[136:137], v[136:137]
	v_pk_mul_f32 v[142:143], v[138:139], v[138:139]
	v_mul_f32_e32 v145, v147, v145
	v_mul_f32_e32 v151, 0xc0135761, v151
	v_mul_f32_e32 v152, v149, v152
	v_fma_f32 v140, v140, s97, 1.0
	v_fma_f32 v141, v141, s97, 1.0
	v_fma_f32 v142, v142, s97, 1.0
	v_fma_f32 v143, v143, s97, 1.0
	v_mul_f32_e32 v145, 0xc0135761, v145
	v_exp_f32_e32 v151, v151
	v_mul_f32_e32 v152, 0xc0135761, v152
	v_mul_f32_e32 v140, v136, v140
	v_mul_f32_e32 v141, v137, v141
	v_mul_f32_e32 v142, v138, v142
	v_mul_f32_e32 v143, v139, v143
	v_exp_f32_e32 v145, v145
	v_exp_f32_e32 v153, v152
	v_mul_f32_e32 v140, 0xc0135761, v140
	v_mul_f32_e32 v141, 0xc0135761, v141
	v_mul_f32_e32 v142, 0xc0135761, v142
	v_mul_f32_e32 v143, 0xc0135761, v143
	v_exp_f32_e32 v140, v140
	v_exp_f32_e32 v141, v141
	v_exp_f32_e32 v142, v142
	v_exp_f32_e32 v143, v143
	v_add_f32_e32 v151, 1.0, v151
	v_add_f32_e32 v145, 1.0, v145
	v_rcp_f32_e32 v152, v151
	v_add_f32_e32 v151, 1.0, v153
	v_rcp_f32_e32 v153, v151
	v_rcp_f32_e32 v151, v145
	v_add_f32_e32 v140, 1.0, v140
	v_add_f32_e32 v141, 1.0, v141
	v_add_f32_e32 v142, 1.0, v142
	v_add_f32_e32 v143, 1.0, v143
	v_rcp_f32_e32 v140, v140
	v_rcp_f32_e32 v142, v142
	v_rcp_f32_e32 v143, v143
	v_rcp_f32_e32 v141, v141
	v_pk_mul_f32 v[146:147], v[146:147], v[150:151]
	v_ashrrev_i32_e32 v145, 31, v144
	v_pk_mul_f32 v[132:133], v[132:133], v[146:147]
	v_pk_mul_f32 v[138:139], v[138:139], v[142:143]
	v_pk_mul_f32 v[136:137], v[136:137], v[140:141]
	v_pk_mul_f32 v[138:139], v[130:131], v[138:139]
	v_pk_mul_f32 v[130:131], v[128:129], v[136:137]
	v_cvt_pk_bf16_f32 v128, v132, v133
	v_lshlrev_b64 v[132:133], 13, v[144:145]
	v_lshl_add_u64 v[132:133], s[44:45], 0, v[132:133]
	v_pk_mul_f32 v[148:149], v[148:149], v[152:153]
	v_lshl_add_u64 v[132:133], v[176:177], 1, v[132:133]
	v_pk_mul_f32 v[134:135], v[134:135], v[148:149]
	s_nop 0
	v_cvt_pk_bf16_f32 v129, v134, v135
	v_cvt_pk_bf16_f32 v130, v130, v131
	v_cvt_pk_bf16_f32 v131, v138, v139
	global_store_dwordx4 v[132:133], v[128:131], off nt

;     __device__ __forceinline__ void operator()(const f32x4 (&acc)[2][2][4][2], const Unit& u, int wr, int wc, int fr, int fq) const {
;     ...
;         for (int ai = 0; ai < 2; ++ai)
; #pragma unroll
;             for (int m = 0; m < 4; ++m) {
;                 bool valid; int grow; bool zp = false, zn = false;
;                 if (!fix) { valid = !((ai == 0 && m == 0 && fr == 0) || (ai == 1 && m == 3 && fr == 15)); grow = u.pm * BM + wr * HALF + ai * 64 + m * 16 + fr; }
;                 else { const int R = (u.pm - nmain) * BM + wr * HALF + ai * 64 + m * 16 + fr; const int grp = R >> 2, pos = R & 3;
;                     const bool ss = (grp < 256) ? ((grp & 15) == 0) : (grp == 256);
;                     valid = (pos == 1) || (pos == 2); grow = (pos == 1) ? ((grp * 128 - 1 + mrows) % mrows) : (grp * 128);
;                     zn = (pos == 1) && ss; zp = (pos == 2) && ss; }
;                 f32x4 res[2];
;                 const float fzp = zp ? 0.f : 1.f, fzn = zn ? 0.f : 1.f;
; #pragma unroll
;                 for (int n = 0; n < 2; ++n) {
;                     const f32x4 g = acc[ai][0][m][n], up = acc[ai][1][m][n];
;                     f32x4 tp = g, tn = g;
;                     if (!fix) { const f32x4 gm = (m > 0) ? acc[ai][0][m - 1][n] : acc[ai ^ 1][0][3][n], gx = (m < 3) ? acc[ai][0][m + 1][n] : acc[ai ^ 1][0][0][n];
;                         tp = (fr == 15) ? gm : g; tn = (fr == 0) ? gx : g; }
;                     f32x4 gp, gn;
; #pragma unroll
;                     for (int j = 0; j < 4; ++j) { gp[j] = dpp_ror1(tp[j]); gn[j] = dpp_ror15(tn[j]); }
;                     const f32x4 cv = (w0[n] * fzp) * gp + (w1[n] * g + ((w2[n] * fzn) * gn + bb[n]));
;                     const f32x4 inner = cv * (cv * cv * 0.044715f + 1.0f) * (-2.0f * 0.7978845608028654f * 1.4426950408889634f);
;                     f32x4 sg;
; #pragma unroll
;                     for (int j = 0; j < 4; ++j) sg[j] = __builtin_amdgcn_rcpf(1.0f + __builtin_amdgcn_exp2f(inner[j]));
;                     res[n] = cv * sg * up;
;                 }
;                 if (valid) { u32x4 w; w.x = cvt_pk_bf16(res[0][0], res[0][1]); w.y = cvt_pk_bf16(res[0][2], res[0][3]); w.z = cvt_pk_bf16(res[1][0], res[1][1]); w.w = cvt_pk_bf16(res[1][2], res[1][3]);
;                     __builtin_nontemporal_store(w, (u32x4*)(ACT + (size_t)grow * 4096 + ch0)); }
.LBB0_655:
	v_cndmask_b32_e64 v133, v110, v62, s[18:19]
	v_cndmask_b32_e64 v127, v111, v127, s[16:17]
	v_cndmask_b32_e64 v131, v108, v60, s[18:19]
	v_mov_b32_dpp v136, v133 row_ror:15 row_mask:0xf bank_mask:0xf
	v_cndmask_b32_e64 v125, v109, v125, s[16:17]
	v_mov_b32_dpp v133, v127 row_ror:1 row_mask:0xf bank_mask:0xf
	v_cndmask_b32_e64 v127, v107, v123, s[16:17]
	v_cndmask_b32_e64 v123, v106, v122, s[16:17]
	v_cndmask_b32_e64 v122, v105, v121, s[16:17]
	v_cndmask_b32_e64 v121, v104, v120, s[16:17]
	v_cndmask_b32_e64 v124, v108, v124, s[16:17]
	v_cndmask_b32_e64 v132, v109, v61, s[18:19]
	v_mov_b32_dpp v134, v131 row_ror:15 row_mask:0xf bank_mask:0xf
	v_mov_b32_dpp v120, v121 row_ror:1 row_mask:0xf bank_mask:0xf
	v_cndmask_b32_e64 v126, v110, v126, s[16:17]
	v_mov_b32_dpp v130, v124 row_ror:1 row_mask:0xf bank_mask:0xf
	v_mov_b32_dpp v131, v125 row_ror:1 row_mask:0xf bank_mask:0xf
	v_mov_b32_dpp v135, v132 row_ror:15 row_mask:0xf bank_mask:0xf
	v_cndmask_b32_e64 v125, v104, v56, s[18:19]
	v_mov_b32_dpp v121, v122 row_ror:1 row_mask:0xf bank_mask:0xf
	v_cndmask_b32_e64 v129, v111, v63, s[18:19]
	v_mov_b32_dpp v132, v126 row_ror:1 row_mask:0xf bank_mask:0xf
	v_cndmask_b32_e64 v126, v105, v57, s[18:19]
	v_mov_b32_dpp v124, v125 row_ror:15 row_mask:0xf bank_mask:0xf
	v_mov_b32_dpp v122, v123 row_ror:1 row_mask:0xf bank_mask:0xf
	v_mov_b32_dpp v137, v129 row_ror:15 row_mask:0xf bank_mask:0xf
	v_cndmask_b32_e64 v129, v107, v59, s[18:19]
	v_cndmask_b32_e64 v138, v106, v58, s[18:19]
	v_mov_b32_dpp v125, v126 row_ror:15 row_mask:0xf bank_mask:0xf
	v_mov_b32_dpp v123, v127 row_ror:1 row_mask:0xf bank_mask:0xf
	v_mov_b32_dpp v126, v138 row_ror:15 row_mask:0xf bank_mask:0xf
	s_nop 0
	v_mov_b32_dpp v127, v129 row_ror:15 row_mask:0xf bank_mask:0xf
	s_and_saveexec_b64 s[80:81], s[82:83]
	s_cbranch_execz .LBB0_657
	v_pk_fma_f32 v[134:135], v[96:97], v[134:135], v[100:101]
	v_pk_fma_f32 v[136:137], v[98:99], v[136:137], v[102:103]
	v_pk_fma_f32 v[134:135], v[108:109], v[92:93], v[134:135]
	v_pk_fma_f32 v[136:137], v[110:111], v[94:95], v[136:137]
	v_pk_fma_f32 v[130:131], v[88:89], v[130:131], v[134:135]
	v_pk_fma_f32 v[132:133], v[90:91], v[132:133], v[136:137]
	v_pk_mul_f32 v[134:135], v[130:131], v[130:131]
	v_pk_fma_f32 v[126:127], v[82:83], v[126:127], v[86:87]
	v_fma_f32 v129, v134, s97, 1.0
	v_mul_f32_e32 v129, v130, v129
	v_mul_f32_e32 v129, 0xc0135761, v129
	v_exp_f32_e32 v129, v129
	v_pk_fma_f32 v[124:125], v[80:81], v[124:125], v[84:85]
	v_pk_mul_f32 v[136:137], v[132:133], v[132:133]
	v_pk_fma_f32 v[124:125], v[104:105], v[76:77], v[124:125]
	v_add_f32_e32 v129, 1.0, v129
	v_pk_fma_f32 v[126:127], v[106:107], v[78:79], v[126:127]
	v_rcp_f32_e32 v134, v129
	v_fma_f32 v129, v135, s97, 1.0
	v_fma_f32 v135, v136, s97, 1.0
	v_pk_fma_f32 v[120:121], v[72:73], v[120:121], v[124:125]
	v_pk_fma_f32 v[122:123], v[74:75], v[122:123], v[126:127]
	v_mul_f32_e32 v135, v132, v135
	v_fma_f32 v136, v137, s97, 1.0
	v_pk_mul_f32 v[124:125], v[120:121], v[120:121]
	v_pk_mul_f32 v[126:127], v[122:123], v[122:123]
	v_mul_f32_e32 v129, v131, v129
	v_mul_f32_e32 v135, 0xc0135761, v135
	v_mul_f32_e32 v136, v133, v136
	v_fma_f32 v124, v124, s97, 1.0
	v_fma_f32 v125, v125, s97, 1.0
	v_fma_f32 v126, v126, s97, 1.0
	v_fma_f32 v127, v127, s97, 1.0
	v_mul_f32_e32 v129, 0xc0135761, v129
	v_exp_f32_e32 v135, v135
	v_mul_f32_e32 v136, 0xc0135761, v136
	v_mul_f32_e32 v124, v120, v124
	v_mul_f32_e32 v125, v121, v125
	v_mul_f32_e32 v126, v122, v126
	v_mul_f32_e32 v127, v123, v127
	v_exp_f32_e32 v129, v129
	v_exp_f32_e32 v137, v136
	v_mul_f32_e32 v124, 0xc0135761, v124
	v_mul_f32_e32 v125, 0xc0135761, v125
	v_mul_f32_e32 v126, 0xc0135761, v126
	v_mul_f32_e32 v127, 0xc0135761, v127
	v_exp_f32_e32 v124, v124
	v_exp_f32_e32 v125, v125
	v_exp_f32_e32 v126, v126
	v_exp_f32_e32 v127, v127
	v_add_f32_e32 v135, 1.0, v135
	v_add_f32_e32 v129, 1.0, v129
	v_rcp_f32_e32 v136, v135
	v_add_f32_e32 v135, 1.0, v137
	v_rcp_f32_e32 v137, v135
	v_rcp_f32_e32 v135, v129
	v_add_f32_e32 v124, 1.0, v124
	v_add_f32_e32 v125, 1.0, v125
	v_add_f32_e32 v126, 1.0, v126
	v_add_f32_e32 v127, 1.0, v127
	v_rcp_f32_e32 v124, v124
	v_rcp_f32_e32 v126, v126
	v_rcp_f32_e32 v127, v127
	v_rcp_f32_e32 v125, v125
	v_pk_mul_f32 v[130:131], v[130:131], v[134:135]
	v_ashrrev_i32_e32 v129, 31, v128
	v_pk_mul_f32 v[116:117], v[116:117], v[130:131]
	v_pk_mul_f32 v[122:123], v[122:123], v[126:127]
	v_pk_mul_f32 v[120:121], v[120:121], v[124:125]
	v_pk_mul_f32 v[122:123], v[114:115], v[122:123]
	v_pk_mul_f32 v[114:115], v[112:113], v[120:121]
	v_cvt_pk_bf16_f32 v112, v116, v117
	v_lshlrev_b64 v[116:117], 13, v[128:129]
	v_lshl_add_u64 v[116:117], s[44:45], 0, v[116:117]
	v_pk_mul_f32 v[132:133], v[132:133], v[136:137]
	v_lshl_add_u64 v[116:117], v[176:177], 1, v[116:117]
	v_pk_mul_f32 v[118:119], v[118:119], v[132:133]
	s_nop 0
	v_cvt_pk_bf16_f32 v113, v118, v119
	v_cvt_pk_bf16_f32 v114, v114, v115
	v_cvt_pk_bf16_f32 v115, v122, v123
	global_store_dwordx4 v[116:117], v[112:115], off nt

;     __device__ __forceinline__ void operator()(const f32x4 (&acc)[2][2][4][2], const Unit& u, int wr, int wc, int fr, int fq) const {
;     ...
;         for (int ai = 0; ai < 2; ++ai)
; #pragma unroll
;             for (int m = 0; m < 4; ++m) {
;                 bool valid; int grow; bool zp = false, zn = false;
;                 if (!fix) { valid = !((ai == 0 && m == 0 && fr == 0) || (ai == 1 && m == 3 && fr == 15)); grow = u.pm * BM + wr * HALF + ai * 64 + m * 16 + fr; }
;                 else { const int R = (u.pm - nmain) * BM + wr * HALF + ai * 64 + m * 16 + fr; const int grp = R >> 2, pos = R & 3;
;                     const bool ss = (grp < 256) ? ((grp & 15) == 0) : (grp == 256);
;                     valid = (pos == 1) || (pos == 2); grow = (pos == 1) ? ((grp * 128 - 1 + mrows) % mrows) : (grp * 128);
;                     zn = (pos == 1) && ss; zp = (pos == 2) && ss; }
;                 f32x4 res[2];
;                 const float fzp = zp ? 0.f : 1.f, fzn = zn ? 0.f : 1.f;
; #pragma unroll
;                 for (int n = 0; n < 2; ++n) {
;                     const f32x4 g = acc[ai][0][m][n], up = acc[ai][1][m][n];
;                     f32x4 tp = g, tn = g;
;                     if (!fix) { const f32x4 gm = (m > 0) ? acc[ai][0][m - 1][n] : acc[ai ^ 1][0][3][n], gx = (m < 3) ? acc[ai][0][m + 1][n] : acc[ai ^ 1][0][0][n];
;                         tp = (fr == 15) ? gm : g; tn = (fr == 0) ? gx : g; }
;                     f32x4 gp, gn;
; #pragma unroll
;                     for (int j = 0; j < 4; ++j) { gp[j] = dpp_ror1(tp[j]); gn[j] = dpp_ror15(tn[j]); }
;                     const f32x4 cv = (w0[n] * fzp) * gp + (w1[n] * g + ((w2[n] * fzn) * gn + bb[n]));
;                     const f32x4 inner = cv * (cv * cv * 0.044715f + 1.0f) * (-2.0f * 0.7978845608028654f * 1.4426950408889634f);
;                     f32x4 sg;
; #pragma unroll
;                     for (int j = 0; j < 4; ++j) sg[j] = __builtin_amdgcn_rcpf(1.0f + __builtin_amdgcn_exp2f(inner[j]));
;                     res[n] = cv * sg * up;
;                 }
;                 if (valid) { u32x4 w; w.x = cvt_pk_bf16(res[0][0], res[0][1]); w.y = cvt_pk_bf16(res[0][2], res[0][3]); w.z = cvt_pk_bf16(res[1][0], res[1][1]); w.w = cvt_pk_bf16(res[1][2], res[1][3]);
;                     __builtin_nontemporal_store(w, (u32x4*)(ACT + (size_t)grow * 4096 + ch0)); }
.LBB0_661:
	v_cndmask_b32_e64 v111, v63, v111, s[16:17]
	v_cndmask_b32_e64 v119, v60, v44, s[18:19]
	v_mov_b32_e32 v122, 0
	v_mov_b32_dpp v121, v111 row_ror:1 row_mask:0xf bank_mask:0xf
	v_cndmask_b32_e64 v111, v59, v107, s[16:17]
	v_cndmask_b32_e64 v107, v58, v106, s[16:17]
	v_cndmask_b32_e64 v106, v57, v105, s[16:17]
	v_cndmask_b32_e64 v105, v56, v104, s[16:17]
	v_cndmask_b32_e64 v109, v61, v109, s[16:17]
	v_cndmask_b32_e64 v108, v60, v108, s[16:17]
	v_mov_b32_dpp v122, v119 row_ror:15 row_mask:0xf bank_mask:0xf
	v_mov_b32_dpp v104, v105 row_ror:1 row_mask:0xf bank_mask:0xf
	v_cndmask_b32_e64 v110, v62, v110, s[16:17]
	v_mov_b32_dpp v118, v108 row_ror:1 row_mask:0xf bank_mask:0xf
	v_mov_b32_dpp v119, v109 row_ror:1 row_mask:0xf bank_mask:0xf
	v_cndmask_b32_e64 v109, v56, v40, s[18:19]
	v_mov_b32_dpp v105, v106 row_ror:1 row_mask:0xf bank_mask:0xf
	v_cndmask_b32_e64 v113, v63, v47, s[18:19]
	v_cndmask_b32_e64 v115, v62, v46, s[18:19]
	v_mov_b32_dpp v120, v110 row_ror:1 row_mask:0xf bank_mask:0xf
	v_cndmask_b32_e64 v110, v57, v41, s[18:19]
	v_mov_b32_dpp v108, v109 row_ror:15 row_mask:0xf bank_mask:0xf
	v_mov_b32_dpp v106, v107 row_ror:1 row_mask:0xf bank_mask:0xf
	v_cndmask_b32_e64 v117, v61, v45, s[18:19]
	v_mov_b32_dpp v124, v115 row_ror:15 row_mask:0xf bank_mask:0xf
	v_mov_b32_dpp v125, v113 row_ror:15 row_mask:0xf bank_mask:0xf
	v_cndmask_b32_e64 v113, v59, v43, s[18:19]
	v_cndmask_b32_e64 v115, v58, v42, s[18:19]
	v_mov_b32_dpp v109, v110 row_ror:15 row_mask:0xf bank_mask:0xf
	v_mov_b32_dpp v107, v111 row_ror:1 row_mask:0xf bank_mask:0xf
	v_mov_b32_dpp v123, v117 row_ror:15 row_mask:0xf bank_mask:0xf
	v_mov_b32_dpp v110, v115 row_ror:15 row_mask:0xf bank_mask:0xf
	v_mov_b32_dpp v111, v113 row_ror:15 row_mask:0xf bank_mask:0xf
	s_and_saveexec_b64 s[80:81], s[82:83]
	s_cbranch_execz .LBB0_663
	v_pk_mul_f32 v[132:133], v[96:97], v[114:115] op_sel_hi:[1,0]
	v_pk_mul_f32 v[128:129], v[88:89], v[116:117] op_sel_hi:[1,0]
	v_pk_fma_f32 v[122:123], v[132:133], v[122:123], v[100:101]
	v_pk_mul_f32 v[130:131], v[98:99], v[114:115] op_sel_hi:[1,0]
	v_pk_fma_f32 v[122:123], v[60:61], v[92:93], v[122:123]
	v_pk_fma_f32 v[124:125], v[130:131], v[124:125], v[102:103]
	v_pk_fma_f32 v[118:119], v[128:129], v[118:119], v[122:123]
	v_pk_mul_f32 v[126:127], v[90:91], v[116:117] op_sel_hi:[1,0]
	v_pk_mul_f32 v[122:123], v[118:119], v[118:119]
	v_pk_fma_f32 v[124:125], v[62:63], v[94:95], v[124:125]
	v_fma_f32 v113, v122, s97, 1.0
	v_mul_f32_e32 v113, v118, v113
	v_mul_f32_e32 v113, 0xc0135761, v113
	v_exp_f32_e32 v113, v113
	v_pk_fma_f32 v[120:121], v[126:127], v[120:121], v[124:125]
	v_add_f32_e32 v113, 1.0, v113
	v_pk_mul_f32 v[124:125], v[120:121], v[120:121]
	v_rcp_f32_e32 v122, v113
	v_fma_f32 v115, v124, s97, 1.0
	v_mul_f32_e32 v115, v120, v115
	v_fma_f32 v117, v125, s97, 1.0
	v_mul_f32_e32 v115, 0xc0135761, v115
	v_mul_f32_e32 v117, v121, v117
	v_fma_f32 v113, v123, s97, 1.0
	v_exp_f32_e32 v115, v115
	v_mul_f32_e32 v117, 0xc0135761, v117
	v_mul_f32_e32 v113, v119, v113
	v_exp_f32_e32 v117, v117
	v_mul_f32_e32 v113, 0xc0135761, v113
	v_exp_f32_e32 v113, v113
	v_add_f32_e32 v115, 1.0, v115
	v_rcp_f32_e32 v124, v115
	v_add_f32_e32 v115, 1.0, v117
	v_rcp_f32_e32 v125, v115
	v_add_f32_e32 v113, 1.0, v113
	v_rcp_f32_e32 v123, v113
	v_ashrrev_i32_e32 v113, 31, v112
	v_pk_mul_f32 v[120:121], v[120:121], v[124:125]
	v_pk_mul_f32 v[124:125], v[82:83], v[114:115] op_sel_hi:[1,0]
	v_pk_mul_f32 v[114:115], v[80:81], v[114:115] op_sel_hi:[1,0]
	v_pk_fma_f32 v[110:111], v[124:125], v[110:111], v[86:87]
	v_pk_fma_f32 v[108:109], v[114:115], v[108:109], v[84:85]
	v_pk_mul_f32 v[118:119], v[118:119], v[122:123]
	v_pk_mul_f32 v[122:123], v[74:75], v[116:117] op_sel_hi:[1,0]
	v_pk_mul_f32 v[116:117], v[72:73], v[116:117] op_sel_hi:[1,0]
	v_pk_fma_f32 v[108:109], v[56:57], v[76:77], v[108:109]
	v_pk_fma_f32 v[110:111], v[58:59], v[78:79], v[110:111]
	v_pk_fma_f32 v[104:105], v[116:117], v[104:105], v[108:109]
	v_pk_fma_f32 v[106:107], v[122:123], v[106:107], v[110:111]
	v_pk_mul_f32 v[108:109], v[104:105], v[104:105]
	v_pk_mul_f32 v[110:111], v[106:107], v[106:107]
	v_fma_f32 v108, v108, s97, 1.0
	v_fma_f32 v109, v109, s97, 1.0
	v_fma_f32 v110, v110, s97, 1.0
	v_fma_f32 v111, v111, s97, 1.0
	v_mul_f32_e32 v108, v104, v108
	v_mul_f32_e32 v109, v105, v109
	v_mul_f32_e32 v110, v106, v110
	v_mul_f32_e32 v111, v107, v111
	v_mul_f32_e32 v108, 0xc0135761, v108
	v_mul_f32_e32 v109, 0xc0135761, v109
	v_mul_f32_e32 v110, 0xc0135761, v110
	v_mul_f32_e32 v111, 0xc0135761, v111
	v_exp_f32_e32 v108, v108
	v_exp_f32_e32 v109, v109
	v_exp_f32_e32 v110, v110
	v_exp_f32_e32 v111, v111
	v_add_f32_e32 v108, 1.0, v108
	v_add_f32_e32 v109, 1.0, v109
	v_add_f32_e32 v110, 1.0, v110
	v_add_f32_e32 v111, 1.0, v111
	v_rcp_f32_e32 v108, v108
	v_rcp_f32_e32 v110, v110
	v_rcp_f32_e32 v111, v111
	v_rcp_f32_e32 v109, v109
	v_pk_mul_f32 v[68:69], v[68:69], v[118:119]
	v_pk_mul_f32 v[70:71], v[70:71], v[120:121]
	v_pk_mul_f32 v[106:107], v[106:107], v[110:111]
	v_pk_mul_f32 v[104:105], v[104:105], v[108:109]
	v_pk_mul_f32 v[106:107], v[66:67], v[106:107]
	v_pk_mul_f32 v[66:67], v[64:65], v[104:105]
	v_cvt_pk_bf16_f32 v64, v68, v69
	v_lshlrev_b64 v[68:69], 13, v[112:113]
	v_lshl_add_u64 v[68:69], s[44:45], 0, v[68:69]
	v_lshl_add_u64 v[68:69], v[176:177], 1, v[68:69]
	v_cvt_pk_bf16_f32 v65, v70, v71
	v_cvt_pk_bf16_f32 v66, v66, v67
	v_cvt_pk_bf16_f32 v67, v106, v107
	global_store_dwordx4 v[68:69], v[64:67], off nt

;     __device__ __forceinline__ void operator()(const f32x4 (&acc)[2][2][4][2], const Unit& u, int wr, int wc, int fr, int fq) const {
;     ...
;         for (int ai = 0; ai < 2; ++ai)
; #pragma unroll
;             for (int m = 0; m < 4; ++m) {
;                 bool valid; int grow; bool zp = false, zn = false;
;                 if (!fix) { valid = !((ai == 0 && m == 0 && fr == 0) || (ai == 1 && m == 3 && fr == 15)); grow = u.pm * BM + wr * HALF + ai * 64 + m * 16 + fr; }
;                 else { const int R = (u.pm - nmain) * BM + wr * HALF + ai * 64 + m * 16 + fr; const int grp = R >> 2, pos = R & 3;
;                     const bool ss = (grp < 256) ? ((grp & 15) == 0) : (grp == 256);
;                     valid = (pos == 1) || (pos == 2); grow = (pos == 1) ? ((grp * 128 - 1 + mrows) % mrows) : (grp * 128);
;                     zn = (pos == 1) && ss; zp = (pos == 2) && ss; }
;                 f32x4 res[2];
;                 const float fzp = zp ? 0.f : 1.f, fzn = zn ? 0.f : 1.f;
; #pragma unroll
;                 for (int n = 0; n < 2; ++n) {
;                     const f32x4 g = acc[ai][0][m][n], up = acc[ai][1][m][n];
;                     f32x4 tp = g, tn = g;
;                     if (!fix) { const f32x4 gm = (m > 0) ? acc[ai][0][m - 1][n] : acc[ai ^ 1][0][3][n], gx = (m < 3) ? acc[ai][0][m + 1][n] : acc[ai ^ 1][0][0][n];
;                         tp = (fr == 15) ? gm : g; tn = (fr == 0) ? gx : g; }
;                     f32x4 gp, gn;
; #pragma unroll
;                     for (int j = 0; j < 4; ++j) { gp[j] = dpp_ror1(tp[j]); gn[j] = dpp_ror15(tn[j]); }
;                     const f32x4 cv = (w0[n] * fzp) * gp + (w1[n] * g + ((w2[n] * fzn) * gn + bb[n]));
;                     const f32x4 inner = cv * (cv * cv * 0.044715f + 1.0f) * (-2.0f * 0.7978845608028654f * 1.4426950408889634f);
;                     f32x4 sg;
; #pragma unroll
;                     for (int j = 0; j < 4; ++j) sg[j] = __builtin_amdgcn_rcpf(1.0f + __builtin_amdgcn_exp2f(inner[j]));
;                     res[n] = cv * sg * up;
;                 }
;                 if (valid) { u32x4 w; w.x = cvt_pk_bf16(res[0][0], res[0][1]); w.y = cvt_pk_bf16(res[0][2], res[0][3]); w.z = cvt_pk_bf16(res[1][0], res[1][1]); w.w = cvt_pk_bf16(res[1][2], res[1][3]);
;                     __builtin_nontemporal_store(w, (u32x4*)(ACT + (size_t)grow * 4096 + ch0)); }
.LBB0_669:
	v_cndmask_b32_e64 v69, v46, v22, s[18:19]
	v_cndmask_b32_e64 v63, v47, v63, s[16:17]
	v_cndmask_b32_e64 v67, v44, v20, s[18:19]
	v_mov_b32_dpp v104, v69 row_ror:15 row_mask:0xf bank_mask:0xf
	v_cndmask_b32_e64 v61, v45, v61, s[16:17]
	v_mov_b32_dpp v69, v63 row_ror:1 row_mask:0xf bank_mask:0xf
	v_cndmask_b32_e64 v63, v43, v59, s[16:17]
	v_cndmask_b32_e64 v59, v42, v58, s[16:17]
	v_cndmask_b32_e64 v58, v41, v57, s[16:17]
	v_cndmask_b32_e64 v57, v40, v56, s[16:17]
	v_cndmask_b32_e64 v60, v44, v60, s[16:17]
	v_cndmask_b32_e64 v68, v45, v21, s[18:19]
	v_mov_b32_dpp v70, v67 row_ror:15 row_mask:0xf bank_mask:0xf
	v_mov_b32_dpp v56, v57 row_ror:1 row_mask:0xf bank_mask:0xf
	v_cndmask_b32_e64 v62, v46, v62, s[16:17]
	v_mov_b32_dpp v66, v60 row_ror:1 row_mask:0xf bank_mask:0xf
	v_mov_b32_dpp v67, v61 row_ror:1 row_mask:0xf bank_mask:0xf
	v_mov_b32_dpp v71, v68 row_ror:15 row_mask:0xf bank_mask:0xf
	v_cndmask_b32_e64 v61, v40, v16, s[18:19]
	v_mov_b32_dpp v57, v58 row_ror:1 row_mask:0xf bank_mask:0xf
	v_cndmask_b32_e64 v65, v47, v23, s[18:19]
	v_mov_b32_dpp v68, v62 row_ror:1 row_mask:0xf bank_mask:0xf
	v_cndmask_b32_e64 v62, v41, v17, s[18:19]
	v_mov_b32_dpp v60, v61 row_ror:15 row_mask:0xf bank_mask:0xf
	v_mov_b32_dpp v58, v59 row_ror:1 row_mask:0xf bank_mask:0xf
	v_mov_b32_dpp v105, v65 row_ror:15 row_mask:0xf bank_mask:0xf
	v_cndmask_b32_e64 v65, v43, v19, s[18:19]
	v_cndmask_b32_e64 v107, v42, v18, s[18:19]
	v_mov_b32_dpp v61, v62 row_ror:15 row_mask:0xf bank_mask:0xf
	v_mov_b32_dpp v59, v63 row_ror:1 row_mask:0xf bank_mask:0xf
	v_mov_b32_dpp v62, v107 row_ror:15 row_mask:0xf bank_mask:0xf
	s_nop 0
	v_mov_b32_dpp v63, v65 row_ror:15 row_mask:0xf bank_mask:0xf
	s_and_saveexec_b64 s[64:65], s[80:81]
	s_cbranch_execz .LBB0_671
	v_pk_fma_f32 v[70:71], v[96:97], v[70:71], v[100:101]
	v_pk_fma_f32 v[104:105], v[98:99], v[104:105], v[102:103]
	v_pk_fma_f32 v[70:71], v[44:45], v[92:93], v[70:71]
	v_pk_fma_f32 v[104:105], v[46:47], v[94:95], v[104:105]
	v_pk_fma_f32 v[66:67], v[88:89], v[66:67], v[70:71]
	v_pk_fma_f32 v[68:69], v[90:91], v[68:69], v[104:105]
	v_pk_mul_f32 v[70:71], v[66:67], v[66:67]
	v_pk_fma_f32 v[62:63], v[82:83], v[62:63], v[86:87]
	v_fma_f32 v65, v70, s97, 1.0
	v_mul_f32_e32 v65, v66, v65
	v_mul_f32_e32 v65, 0xc0135761, v65
	v_exp_f32_e32 v65, v65
	v_pk_fma_f32 v[60:61], v[80:81], v[60:61], v[84:85]
	v_pk_mul_f32 v[104:105], v[68:69], v[68:69]
	v_pk_fma_f32 v[60:61], v[40:41], v[76:77], v[60:61]
	v_add_f32_e32 v65, 1.0, v65
	v_pk_fma_f32 v[62:63], v[42:43], v[78:79], v[62:63]
	v_rcp_f32_e32 v70, v65
	v_fma_f32 v65, v71, s97, 1.0
	v_fma_f32 v71, v104, s97, 1.0
	v_pk_fma_f32 v[56:57], v[72:73], v[56:57], v[60:61]
	v_pk_fma_f32 v[58:59], v[74:75], v[58:59], v[62:63]
	v_mul_f32_e32 v71, v68, v71
	v_fma_f32 v104, v105, s97, 1.0
	v_pk_mul_f32 v[60:61], v[56:57], v[56:57]
	v_pk_mul_f32 v[62:63], v[58:59], v[58:59]
	v_mul_f32_e32 v65, v67, v65
	v_mul_f32_e32 v71, 0xc0135761, v71
	v_mul_f32_e32 v104, v69, v104
	v_fma_f32 v60, v60, s97, 1.0
	v_fma_f32 v61, v61, s97, 1.0
	v_fma_f32 v62, v62, s97, 1.0
	v_fma_f32 v63, v63, s97, 1.0
	v_mul_f32_e32 v65, 0xc0135761, v65
	v_exp_f32_e32 v71, v71
	v_mul_f32_e32 v104, 0xc0135761, v104
	v_mul_f32_e32 v60, v56, v60
	v_mul_f32_e32 v61, v57, v61
	v_mul_f32_e32 v62, v58, v62
	v_mul_f32_e32 v63, v59, v63
	v_exp_f32_e32 v65, v65
	v_exp_f32_e32 v105, v104
	v_mul_f32_e32 v60, 0xc0135761, v60
	v_mul_f32_e32 v61, 0xc0135761, v61
	v_mul_f32_e32 v62, 0xc0135761, v62
	v_mul_f32_e32 v63, 0xc0135761, v63
	v_exp_f32_e32 v60, v60
	v_exp_f32_e32 v61, v61
	v_exp_f32_e32 v62, v62
	v_exp_f32_e32 v63, v63
	v_add_f32_e32 v71, 1.0, v71
	v_add_f32_e32 v65, 1.0, v65
	v_rcp_f32_e32 v104, v71
	v_add_f32_e32 v71, 1.0, v105
	v_rcp_f32_e32 v105, v71
	v_rcp_f32_e32 v71, v65
	v_add_f32_e32 v60, 1.0, v60
	v_add_f32_e32 v61, 1.0, v61
	v_add_f32_e32 v62, 1.0, v62
	v_add_f32_e32 v63, 1.0, v63
	v_rcp_f32_e32 v60, v60
	v_rcp_f32_e32 v62, v62
	v_rcp_f32_e32 v63, v63
	v_rcp_f32_e32 v61, v61
	v_pk_mul_f32 v[66:67], v[66:67], v[70:71]
	v_ashrrev_i32_e32 v65, 31, v64
	v_pk_mul_f32 v[52:53], v[52:53], v[66:67]
	v_pk_mul_f32 v[58:59], v[58:59], v[62:63]
	v_pk_mul_f32 v[56:57], v[56:57], v[60:61]
	v_pk_mul_f32 v[58:59], v[50:51], v[58:59]
	v_pk_mul_f32 v[50:51], v[48:49], v[56:57]
	v_cvt_pk_bf16_f32 v48, v52, v53
	v_lshlrev_b64 v[52:53], 13, v[64:65]
	v_lshl_add_u64 v[52:53], s[44:45], 0, v[52:53]
	v_pk_mul_f32 v[68:69], v[68:69], v[104:105]
	v_lshl_add_u64 v[52:53], v[176:177], 1, v[52:53]
	v_pk_mul_f32 v[54:55], v[54:55], v[68:69]
	s_nop 0
	v_cvt_pk_bf16_f32 v49, v54, v55
	v_cvt_pk_bf16_f32 v50, v50, v51
	v_cvt_pk_bf16_f32 v51, v58, v59
	global_store_dwordx4 v[52:53], v[48:51], off nt

;     __device__ __forceinline__ void operator()(const f32x4 (&acc)[2][2][4][2], const Unit& u, int wr, int wc, int fr, int fq) const {
;     ...
;         for (int ai = 0; ai < 2; ++ai)
; #pragma unroll
;             for (int m = 0; m < 4; ++m) {
;                 bool valid; int grow; bool zp = false, zn = false;
;                 if (!fix) { valid = !((ai == 0 && m == 0 && fr == 0) || (ai == 1 && m == 3 && fr == 15)); grow = u.pm * BM + wr * HALF + ai * 64 + m * 16 + fr; }
;                 else { const int R = (u.pm - nmain) * BM + wr * HALF + ai * 64 + m * 16 + fr; const int grp = R >> 2, pos = R & 3;
;                     const bool ss = (grp < 256) ? ((grp & 15) == 0) : (grp == 256);
;                     valid = (pos == 1) || (pos == 2); grow = (pos == 1) ? ((grp * 128 - 1 + mrows) % mrows) : (grp * 128);
;                     zn = (pos == 1) && ss; zp = (pos == 2) && ss; }
;                 f32x4 res[2];
;                 const float fzp = zp ? 0.f : 1.f, fzn = zn ? 0.f : 1.f;
; #pragma unroll
;                 for (int n = 0; n < 2; ++n) {
;                     const f32x4 g = acc[ai][0][m][n], up = acc[ai][1][m][n];
;                     f32x4 tp = g, tn = g;
;                     if (!fix) { const f32x4 gm = (m > 0) ? acc[ai][0][m - 1][n] : acc[ai ^ 1][0][3][n], gx = (m < 3) ? acc[ai][0][m + 1][n] : acc[ai ^ 1][0][0][n];
;                         tp = (fr == 15) ? gm : g; tn = (fr == 0) ? gx : g; }
;                     f32x4 gp, gn;
; #pragma unroll
;                     for (int j = 0; j < 4; ++j) { gp[j] = dpp_ror1(tp[j]); gn[j] = dpp_ror15(tn[j]); }
;                     const f32x4 cv = (w0[n] * fzp) * gp + (w1[n] * g + ((w2[n] * fzn) * gn + bb[n]));
;                     const f32x4 inner = cv * (cv * cv * 0.044715f + 1.0f) * (-2.0f * 0.7978845608028654f * 1.4426950408889634f);
;                     f32x4 sg;
; #pragma unroll
;                     for (int j = 0; j < 4; ++j) sg[j] = __builtin_amdgcn_rcpf(1.0f + __builtin_amdgcn_exp2f(inner[j]));
;                     res[n] = cv * sg * up;
;                 }
;                 if (valid) { u32x4 w; w.x = cvt_pk_bf16(res[0][0], res[0][1]); w.y = cvt_pk_bf16(res[0][2], res[0][3]); w.z = cvt_pk_bf16(res[1][0], res[1][1]); w.w = cvt_pk_bf16(res[1][2], res[1][3]);
;                     __builtin_nontemporal_store(w, (u32x4*)(ACT + (size_t)grow * 4096 + ch0)); }
.LBB0_677:
	v_cndmask_b32_e64 v53, v22, v14, s[18:19]
	v_cndmask_b32_e64 v47, v23, v47, s[16:17]
	v_cndmask_b32_e64 v51, v20, v12, s[18:19]
	v_mov_b32_dpp v56, v53 row_ror:15 row_mask:0xf bank_mask:0xf
	v_cndmask_b32_e64 v45, v21, v45, s[16:17]
	v_mov_b32_dpp v53, v47 row_ror:1 row_mask:0xf bank_mask:0xf
	v_cndmask_b32_e64 v47, v19, v43, s[16:17]
	v_cndmask_b32_e64 v43, v18, v42, s[16:17]
	v_cndmask_b32_e64 v42, v17, v41, s[16:17]
	v_cndmask_b32_e64 v41, v16, v40, s[16:17]
	v_cndmask_b32_e64 v44, v20, v44, s[16:17]
	v_cndmask_b32_e64 v52, v21, v13, s[18:19]
	v_mov_b32_dpp v54, v51 row_ror:15 row_mask:0xf bank_mask:0xf
	v_mov_b32_dpp v40, v41 row_ror:1 row_mask:0xf bank_mask:0xf
	v_cndmask_b32_e64 v46, v22, v46, s[16:17]
	v_mov_b32_dpp v50, v44 row_ror:1 row_mask:0xf bank_mask:0xf
	v_mov_b32_dpp v51, v45 row_ror:1 row_mask:0xf bank_mask:0xf
	v_mov_b32_dpp v55, v52 row_ror:15 row_mask:0xf bank_mask:0xf
	v_cndmask_b32_e64 v45, v16, v8, s[18:19]
	v_mov_b32_dpp v41, v42 row_ror:1 row_mask:0xf bank_mask:0xf
	v_cndmask_b32_e64 v49, v23, v15, s[18:19]
	v_mov_b32_dpp v52, v46 row_ror:1 row_mask:0xf bank_mask:0xf
	v_cndmask_b32_e64 v46, v17, v9, s[18:19]
	v_mov_b32_dpp v44, v45 row_ror:15 row_mask:0xf bank_mask:0xf
	v_mov_b32_dpp v42, v43 row_ror:1 row_mask:0xf bank_mask:0xf
	v_mov_b32_dpp v57, v49 row_ror:15 row_mask:0xf bank_mask:0xf
	v_cndmask_b32_e64 v49, v19, v11, s[18:19]
	v_cndmask_b32_e64 v58, v18, v10, s[18:19]
	v_mov_b32_dpp v45, v46 row_ror:15 row_mask:0xf bank_mask:0xf
	v_mov_b32_dpp v43, v47 row_ror:1 row_mask:0xf bank_mask:0xf
	v_mov_b32_dpp v46, v58 row_ror:15 row_mask:0xf bank_mask:0xf
	s_nop 0
	v_mov_b32_dpp v47, v49 row_ror:15 row_mask:0xf bank_mask:0xf
	s_and_saveexec_b64 s[64:65], s[80:81]
	s_cbranch_execz .LBB0_679
	v_pk_fma_f32 v[54:55], v[96:97], v[54:55], v[100:101]
	v_pk_fma_f32 v[56:57], v[98:99], v[56:57], v[102:103]
	v_pk_fma_f32 v[54:55], v[20:21], v[92:93], v[54:55]
	v_pk_fma_f32 v[56:57], v[22:23], v[94:95], v[56:57]
	v_pk_fma_f32 v[50:51], v[88:89], v[50:51], v[54:55]
	v_pk_fma_f32 v[52:53], v[90:91], v[52:53], v[56:57]
	v_pk_mul_f32 v[54:55], v[50:51], v[50:51]
	v_pk_fma_f32 v[46:47], v[82:83], v[46:47], v[86:87]
	v_fma_f32 v49, v54, s97, 1.0
	v_mul_f32_e32 v49, v50, v49
	v_mul_f32_e32 v49, 0xc0135761, v49
	v_exp_f32_e32 v49, v49
	v_pk_fma_f32 v[44:45], v[80:81], v[44:45], v[84:85]
	v_pk_mul_f32 v[56:57], v[52:53], v[52:53]
	v_pk_fma_f32 v[44:45], v[16:17], v[76:77], v[44:45]
	v_add_f32_e32 v49, 1.0, v49
	v_pk_fma_f32 v[46:47], v[18:19], v[78:79], v[46:47]
	v_rcp_f32_e32 v54, v49
	v_fma_f32 v49, v55, s97, 1.0
	v_fma_f32 v55, v56, s97, 1.0
	v_pk_fma_f32 v[40:41], v[72:73], v[40:41], v[44:45]
	v_pk_fma_f32 v[42:43], v[74:75], v[42:43], v[46:47]
	v_mul_f32_e32 v55, v52, v55
	v_fma_f32 v56, v57, s97, 1.0
	v_pk_mul_f32 v[44:45], v[40:41], v[40:41]
	v_pk_mul_f32 v[46:47], v[42:43], v[42:43]
	v_mul_f32_e32 v49, v51, v49
	v_mul_f32_e32 v55, 0xc0135761, v55
	v_mul_f32_e32 v56, v53, v56
	v_fma_f32 v44, v44, s97, 1.0
	v_fma_f32 v45, v45, s97, 1.0
	v_fma_f32 v46, v46, s97, 1.0
	v_fma_f32 v47, v47, s97, 1.0
	v_mul_f32_e32 v49, 0xc0135761, v49
	v_exp_f32_e32 v55, v55
	v_mul_f32_e32 v56, 0xc0135761, v56
	v_mul_f32_e32 v44, v40, v44
	v_mul_f32_e32 v45, v41, v45
	v_mul_f32_e32 v46, v42, v46
	v_mul_f32_e32 v47, v43, v47
	v_exp_f32_e32 v49, v49
	v_exp_f32_e32 v57, v56
	v_mul_f32_e32 v44, 0xc0135761, v44
	v_mul_f32_e32 v45, 0xc0135761, v45
	v_mul_f32_e32 v46, 0xc0135761, v46
	v_mul_f32_e32 v47, 0xc0135761, v47
	v_exp_f32_e32 v44, v44
	v_exp_f32_e32 v45, v45
	v_exp_f32_e32 v46, v46
	v_exp_f32_e32 v47, v47
	v_add_f32_e32 v55, 1.0, v55
	v_add_f32_e32 v49, 1.0, v49
	v_rcp_f32_e32 v56, v55
	v_add_f32_e32 v55, 1.0, v57
	v_rcp_f32_e32 v57, v55
	v_rcp_f32_e32 v55, v49
	v_add_f32_e32 v44, 1.0, v44
	v_add_f32_e32 v45, 1.0, v45
	v_add_f32_e32 v46, 1.0, v46
	v_add_f32_e32 v47, 1.0, v47
	v_rcp_f32_e32 v44, v44
	v_rcp_f32_e32 v46, v46
	v_rcp_f32_e32 v47, v47
	v_rcp_f32_e32 v45, v45
	v_pk_mul_f32 v[50:51], v[50:51], v[54:55]
	v_ashrrev_i32_e32 v49, 31, v48
	v_pk_mul_f32 v[32:33], v[32:33], v[50:51]
	v_pk_mul_f32 v[42:43], v[42:43], v[46:47]
	v_pk_mul_f32 v[40:41], v[40:41], v[44:45]
	v_pk_mul_f32 v[42:43], v[26:27], v[42:43]
	v_pk_mul_f32 v[26:27], v[24:25], v[40:41]
	v_cvt_pk_bf16_f32 v24, v32, v33
	v_lshlrev_b64 v[32:33], 13, v[48:49]
	v_lshl_add_u64 v[32:33], s[44:45], 0, v[32:33]
	v_pk_mul_f32 v[52:53], v[52:53], v[56:57]
	v_lshl_add_u64 v[32:33], v[176:177], 1, v[32:33]
	v_pk_mul_f32 v[34:35], v[34:35], v[52:53]
	s_nop 0
	v_cvt_pk_bf16_f32 v25, v34, v35
	v_cvt_pk_bf16_f32 v26, v26, v27
	v_cvt_pk_bf16_f32 v27, v42, v43
	global_store_dwordx4 v[32:33], v[24:27], off nt

;     __device__ __forceinline__ void operator()(const f32x4 (&acc)[2][2][4][2], const Unit& u, int wr, int wc, int fr, int fq) const {
;     ...
;         for (int ai = 0; ai < 2; ++ai)
; #pragma unroll
;             for (int m = 0; m < 4; ++m) {
;                 bool valid; int grow; bool zp = false, zn = false;
;                 if (!fix) { valid = !((ai == 0 && m == 0 && fr == 0) || (ai == 1 && m == 3 && fr == 15)); grow = u.pm * BM + wr * HALF + ai * 64 + m * 16 + fr; }
;                 else { const int R = (u.pm - nmain) * BM + wr * HALF + ai * 64 + m * 16 + fr; const int grp = R >> 2, pos = R & 3;
;                     const bool ss = (grp < 256) ? ((grp & 15) == 0) : (grp == 256);
;                     valid = (pos == 1) || (pos == 2); grow = (pos == 1) ? ((grp * 128 - 1 + mrows) % mrows) : (grp * 128);
;                     zn = (pos == 1) && ss; zp = (pos == 2) && ss; }
;                 f32x4 res[2];
;                 const float fzp = zp ? 0.f : 1.f, fzn = zn ? 0.f : 1.f;
; #pragma unroll
;                 for (int n = 0; n < 2; ++n) {
;                     const f32x4 g = acc[ai][0][m][n], up = acc[ai][1][m][n];
;                     f32x4 tp = g, tn = g;
;                     if (!fix) { const f32x4 gm = (m > 0) ? acc[ai][0][m - 1][n] : acc[ai ^ 1][0][3][n], gx = (m < 3) ? acc[ai][0][m + 1][n] : acc[ai ^ 1][0][0][n];
;                         tp = (fr == 15) ? gm : g; tn = (fr == 0) ? gx : g; }
;                     f32x4 gp, gn;
; #pragma unroll
;                     for (int j = 0; j < 4; ++j) { gp[j] = dpp_ror1(tp[j]); gn[j] = dpp_ror15(tn[j]); }
;                     const f32x4 cv = (w0[n] * fzp) * gp + (w1[n] * g + ((w2[n] * fzn) * gn + bb[n]));
;                     const f32x4 inner = cv * (cv * cv * 0.044715f + 1.0f) * (-2.0f * 0.7978845608028654f * 1.4426950408889634f);
;                     f32x4 sg;
; #pragma unroll
;                     for (int j = 0; j < 4; ++j) sg[j] = __builtin_amdgcn_rcpf(1.0f + __builtin_amdgcn_exp2f(inner[j]));
;                     res[n] = cv * sg * up;
;                 }
;                 if (valid) { u32x4 w; w.x = cvt_pk_bf16(res[0][0], res[0][1]); w.y = cvt_pk_bf16(res[0][2], res[0][3]); w.z = cvt_pk_bf16(res[1][0], res[1][1]); w.w = cvt_pk_bf16(res[1][2], res[1][3]);
;                     __builtin_nontemporal_store(w, (u32x4*)(ACT + (size_t)grow * 4096 + ch0)); }
.LBB0_685:
	v_cndmask_b32_e64 v33, v14, v38, s[18:19]
	v_cndmask_b32_e64 v27, v12, v36, s[18:19]
	v_cndmask_b32_e64 v23, v15, v23, s[16:17]
	v_mov_b32_dpp v36, v33 row_ror:15 row_mask:0xf bank_mask:0xf
	v_cndmask_b32_e64 v21, v13, v21, s[16:17]
	v_cndmask_b32_e64 v20, v12, v20, s[16:17]
	v_mov_b32_dpp v33, v23 row_ror:1 row_mask:0xf bank_mask:0xf
	v_cndmask_b32_e64 v23, v11, v19, s[16:17]
	v_cndmask_b32_e64 v19, v10, v18, s[16:17]
	v_cndmask_b32_e64 v18, v9, v17, s[16:17]
	v_cndmask_b32_e64 v17, v8, v16, s[16:17]
	v_cndmask_b32_e64 v32, v13, v37, s[18:19]
	v_mov_b32_dpp v34, v27 row_ror:15 row_mask:0xf bank_mask:0xf
	v_mov_b32_dpp v16, v17 row_ror:1 row_mask:0xf bank_mask:0xf
	v_cndmask_b32_e64 v22, v14, v22, s[16:17]
	v_mov_b32_dpp v26, v20 row_ror:1 row_mask:0xf bank_mask:0xf
	v_mov_b32_dpp v27, v21 row_ror:1 row_mask:0xf bank_mask:0xf
	v_mov_b32_dpp v35, v32 row_ror:15 row_mask:0xf bank_mask:0xf
	v_cndmask_b32_e64 v21, v8, v28, s[18:19]
	v_mov_b32_dpp v17, v18 row_ror:1 row_mask:0xf bank_mask:0xf
	v_cndmask_b32_e64 v25, v15, v39, s[18:19]
	v_mov_b32_dpp v32, v22 row_ror:1 row_mask:0xf bank_mask:0xf
	v_cndmask_b32_e64 v22, v9, v29, s[18:19]
	v_mov_b32_dpp v20, v21 row_ror:15 row_mask:0xf bank_mask:0xf
	v_mov_b32_dpp v18, v19 row_ror:1 row_mask:0xf bank_mask:0xf
	v_mov_b32_dpp v37, v25 row_ror:15 row_mask:0xf bank_mask:0xf
	v_cndmask_b32_e64 v25, v11, v31, s[18:19]
	v_cndmask_b32_e64 v30, v10, v30, s[18:19]
	v_mov_b32_dpp v21, v22 row_ror:15 row_mask:0xf bank_mask:0xf
	v_mov_b32_dpp v19, v23 row_ror:1 row_mask:0xf bank_mask:0xf
	v_mov_b32_dpp v22, v30 row_ror:15 row_mask:0xf bank_mask:0xf
	s_nop 0
	v_mov_b32_dpp v23, v25 row_ror:15 row_mask:0xf bank_mask:0xf
	s_and_saveexec_b64 s[16:17], s[20:21]
	s_cbranch_execz .LBB0_687
	v_pk_fma_f32 v[30:31], v[96:97], v[34:35], v[100:101]
	v_pk_fma_f32 v[28:29], v[98:99], v[36:37], v[102:103]
	v_pk_fma_f32 v[12:13], v[12:13], v[92:93], v[30:31]
	v_pk_fma_f32 v[14:15], v[14:15], v[94:95], v[28:29]
	v_pk_fma_f32 v[12:13], v[88:89], v[26:27], v[12:13]
	v_pk_fma_f32 v[14:15], v[90:91], v[32:33], v[14:15]
	v_pk_mul_f32 v[26:27], v[12:13], v[12:13]
	v_pk_fma_f32 v[22:23], v[82:83], v[22:23], v[86:87]
	v_fma_f32 v25, v26, s97, 1.0
	v_mul_f32_e32 v25, v12, v25
	v_mul_f32_e32 v25, 0xc0135761, v25
	v_exp_f32_e32 v25, v25
	v_pk_fma_f32 v[20:21], v[80:81], v[20:21], v[84:85]
	v_pk_mul_f32 v[28:29], v[14:15], v[14:15]
	v_pk_fma_f32 v[8:9], v[8:9], v[76:77], v[20:21]
	v_add_f32_e32 v25, 1.0, v25
	v_pk_fma_f32 v[10:11], v[10:11], v[78:79], v[22:23]
	v_rcp_f32_e32 v26, v25
	v_fma_f32 v25, v27, s97, 1.0
	v_fma_f32 v27, v28, s97, 1.0
	v_pk_fma_f32 v[8:9], v[72:73], v[16:17], v[8:9]
	v_pk_fma_f32 v[10:11], v[74:75], v[18:19], v[10:11]
	v_mul_f32_e32 v27, v14, v27
	v_fma_f32 v28, v29, s97, 1.0
	v_pk_mul_f32 v[16:17], v[8:9], v[8:9]
	v_pk_mul_f32 v[18:19], v[10:11], v[10:11]
	v_mul_f32_e32 v25, v13, v25
	v_mul_f32_e32 v27, 0xc0135761, v27
	v_mul_f32_e32 v28, v15, v28
	v_fma_f32 v16, v16, s97, 1.0
	v_fma_f32 v17, v17, s97, 1.0
	v_fma_f32 v18, v18, s97, 1.0
	v_fma_f32 v19, v19, s97, 1.0
	v_mul_f32_e32 v25, 0xc0135761, v25
	v_exp_f32_e32 v27, v27
	v_mul_f32_e32 v28, 0xc0135761, v28
	v_mul_f32_e32 v16, v8, v16
	v_mul_f32_e32 v17, v9, v17
	v_mul_f32_e32 v18, v10, v18
	v_mul_f32_e32 v19, v11, v19
	v_exp_f32_e32 v25, v25
	v_exp_f32_e32 v29, v28
	v_mul_f32_e32 v16, 0xc0135761, v16
	v_mul_f32_e32 v17, 0xc0135761, v17
	v_mul_f32_e32 v18, 0xc0135761, v18
	v_mul_f32_e32 v19, 0xc0135761, v19
	v_exp_f32_e32 v16, v16
	v_exp_f32_e32 v17, v17
	v_exp_f32_e32 v18, v18
	v_exp_f32_e32 v19, v19
	v_add_f32_e32 v27, 1.0, v27
	v_add_f32_e32 v25, 1.0, v25
	v_rcp_f32_e32 v28, v27
	v_add_f32_e32 v27, 1.0, v29
	v_rcp_f32_e32 v29, v27
	v_rcp_f32_e32 v27, v25
	v_add_f32_e32 v16, 1.0, v16
	v_add_f32_e32 v17, 1.0, v17
	v_add_f32_e32 v18, 1.0, v18
	v_add_f32_e32 v19, 1.0, v19
	v_rcp_f32_e32 v16, v16
	v_rcp_f32_e32 v18, v18
	v_rcp_f32_e32 v19, v19
	v_rcp_f32_e32 v17, v17
	v_pk_mul_f32 v[12:13], v[12:13], v[26:27]
	v_ashrrev_i32_e32 v25, 31, v24
	v_pk_mul_f32 v[4:5], v[4:5], v[12:13]
	v_pk_mul_f32 v[10:11], v[10:11], v[18:19]
	v_pk_mul_f32 v[8:9], v[8:9], v[16:17]
	v_pk_mul_f32 v[10:11], v[2:3], v[10:11]
	v_pk_mul_f32 v[2:3], v[0:1], v[8:9]
	v_cvt_pk_bf16_f32 v0, v4, v5
	v_lshlrev_b64 v[4:5], 13, v[24:25]
	v_lshl_add_u64 v[4:5], s[44:45], 0, v[4:5]
	v_pk_mul_f32 v[14:15], v[14:15], v[28:29]
	v_lshl_add_u64 v[4:5], v[176:177], 1, v[4:5]
	v_pk_mul_f32 v[6:7], v[6:7], v[14:15]
	s_nop 0
	v_cvt_pk_bf16_f32 v1, v6, v7
	v_cvt_pk_bf16_f32 v2, v2, v3
	v_cvt_pk_bf16_f32 v3, v10, v11
	global_store_dwordx4 v[4:5], v[0:3], off nt
